# mix_h0_last: mixer queue deals heads 7..1, then the pooling/conv blocks, then head 0 last (dealing-order change only)
# speedup vs baseline: 1.0128x; 1.0128x over previous
; __global__ void __launch_bounds__(NTHR, 2) mk_fwd(Args a) {
;     ...
;                     if (useq) { idx = (int)qw[it & 1]; if (idx >= 160) break; bsel = xg; if (tid == 0) nxt = __hip_atomic_fetch_add(qcnt, 1u, __ATOMIC_RELAXED, __HIP_MEMORY_SCOPE_AGENT); }
;                     else { if (sidx >= BATCH * 160) break; bsel = sidx / 160; idx = sidx % 160; sidx += G; }
;                     const int cls = idx >> 4, e = idx & 15;
.LBB0_309:
	s_cmpk_lt_u32 s16, 0x70
	s_cbranch_scc1 .Lq_map_done
	s_add_i32 s15, s16, 16
	s_sub_i32 s17, s16, 32
	s_cmpk_lt_u32 s16, 0x90
	s_cselect_b32 s16, s15, s17
